# v38 + slimmer LDS-DMA issue block (no m0 save/restore, m0 written by s_add_i32) in both loop variants
# baseline (speedup 1.0000x reference)
.LBB0_1599:
	s_cmp_ge_u32 s68, s59
	s_cbranch_scc1 .Lyka_xtail
	v_add_u32_e32 v0, s72, v208
	ds_read_b128 v[80:83], v0
	ds_read_b128 v[84:87], v0 offset:512
	ds_read_b128 v[6:9], v0 offset:2048
	ds_read_b128 v[112:115], v0 offset:2560
	ds_read_b128 v[10:13], v0 offset:4096
	ds_read_b128 v[116:119], v0 offset:4608
	ds_read_b128 v[2:5], v0 offset:6144
	ds_read_b128 v[120:123], v0 offset:6656
	s_and_b64 vcc, exec, s[8:9]
	s_cbranch_vccnz .LBB0_1608
	s_add_i32 s3, s69, s66
	s_mov_b32 m0, s3
	v_lshl_add_u64 v[14:15], v[168:169], 0, s[28:29]
	global_load_lds_dwordx4 v[168:169], off
	s_add_i32 m0, s3, 0x2000
	s_nop 0
	global_load_lds_dwordx4 v[14:15], off
	v_lshl_add_u64 v[14:15], v[168:169], 0, s[40:41]
	s_add_i32 m0, s3, 0x4000
	s_nop 0
	global_load_lds_dwordx4 v[14:15], off
	v_lshl_add_u64 v[14:15], v[168:169], 0, s[80:81]
	s_add_i32 m0, s3, 0x6000
	s_nop 0
	global_load_lds_dwordx4 v[14:15], off

.Lyka_ytop:
	s_cmp_ge_u32 s68, s59
	s_cbranch_scc1 .Lyka_ytail
	v_add_u32_e32 v0, s72, v208
	ds_read_b128 v[80:83], v0
	ds_read_b128 v[84:87], v0 offset:512
	ds_read_b128 v[6:9], v0 offset:2048
	ds_read_b128 v[112:115], v0 offset:2560
	ds_read_b128 v[10:13], v0 offset:4096
	ds_read_b128 v[116:119], v0 offset:4608
	ds_read_b128 v[2:5], v0 offset:6144
	ds_read_b128 v[120:123], v0 offset:6656
	v_pk_add_f32 v[14:15], v[170:171], 0 op_sel_hi:[1,0]
	v_cvt_pk_bf16_f32 v124, v170, v172
	v_pk_add_f32 v[14:15], v[172:173], v[14:15]
	v_cvt_pk_bf16_f32 v125, v174, v176
	v_pk_add_f32 v[14:15], v[174:175], v[14:15]
	v_cvt_pk_bf16_f32 v126, v178, v180
	v_pk_add_f32 v[14:15], v[176:177], v[14:15]
	v_cvt_pk_bf16_f32 v127, v182, v184
	v_pk_add_f32 v[14:15], v[178:179], v[14:15]
	v_cvt_pk_bf16_f32 v128, v186, v188
	v_pk_add_f32 v[14:15], v[180:181], v[14:15]
	v_cvt_pk_bf16_f32 v129, v190, v192
	v_pk_add_f32 v[14:15], v[182:183], v[14:15]
	v_cvt_pk_bf16_f32 v130, v194, v196
	v_pk_add_f32 v[14:15], v[184:185], v[14:15]
	v_cvt_pk_bf16_f32 v131, v198, v200
	v_pk_add_f32 v[14:15], v[186:187], v[14:15]
	v_cvt_pk_bf16_f32 v132, v171, v173
	v_pk_add_f32 v[14:15], v[188:189], v[14:15]
	v_cvt_pk_bf16_f32 v133, v175, v177
	v_pk_add_f32 v[14:15], v[190:191], v[14:15]
	v_cvt_pk_bf16_f32 v134, v179, v181
	v_pk_add_f32 v[14:15], v[192:193], v[14:15]
	v_cvt_pk_bf16_f32 v135, v183, v185
	v_pk_add_f32 v[14:15], v[194:195], v[14:15]
	v_cvt_pk_bf16_f32 v136, v187, v189
	v_pk_add_f32 v[14:15], v[196:197], v[14:15]
	v_cvt_pk_bf16_f32 v137, v191, v193
	v_pk_add_f32 v[14:15], v[198:199], v[14:15]
	v_cvt_pk_bf16_f32 v138, v195, v197
	v_pk_add_f32 v[14:15], v[200:201], v[14:15]
	v_cvt_pk_bf16_f32 v139, v199, v201
	v_add_f32_e32 v0, v14, v15
	s_waitcnt lgkmcnt(7)
	v_mfma_f32_32x32x16_bf16 v[96:111], v[80:83], v[144:147], 0
	v_add_u32_e32 v14, s71, v209
	s_waitcnt lgkmcnt(6)
	v_mfma_f32_32x32x16_bf16 v[80:95], v[84:87], v[144:147], 0
	s_waitcnt lgkmcnt(4)
	v_mfma_f32_32x32x16_bf16 v[80:95], v[112:115], v[148:151], v[80:95]
	v_mfma_f32_32x32x16_bf16 v[96:111], v[6:9], v[148:151], v[96:111]
	s_waitcnt lgkmcnt(2)
	v_mfma_f32_32x32x16_bf16 v[80:95], v[116:119], v[152:155], v[80:95]
	v_mfma_f32_32x32x16_bf16 v[96:111], v[10:13], v[152:155], v[96:111]
	ds_read_b128 v[6:9], v14 offset:16384
	ds_read_b128 v[10:13], v14 offset:16896
	ds_read_b128 v[112:115], v14 offset:17408
	ds_read_b128 v[116:119], v14 offset:17920
	s_waitcnt lgkmcnt(4)
	v_mfma_f32_32x32x16_bf16 v[80:95], v[120:123], v[156:159], v[80:95]
	v_mfma_f32_32x32x16_bf16 v[96:111], v[2:5], v[156:159], v[96:111]
	s_waitcnt vmcnt(0)
	s_barrier
	s_add_i32 s3, s68, 3
	s_cmp_lt_u32 s3, s67
	s_cbranch_scc0 .Lyka_ynodma
	s_add_i32 s3, s69, s66
	s_mov_b32 m0, s3
	v_lshl_add_u64 v[120:121], v[168:169], 0, s[28:29]
	global_load_lds_dwordx4 v[168:169], off
	s_add_i32 m0, s3, 0x2000
	s_nop 0
	global_load_lds_dwordx4 v[120:121], off
	v_lshl_add_u64 v[120:121], v[168:169], 0, s[40:41]
	s_add_i32 m0, s3, 0x4000
	s_nop 0
	global_load_lds_dwordx4 v[120:121], off
	v_lshl_add_u64 v[120:121], v[168:169], 0, s[80:81]
	s_add_i32 m0, s3, 0x6000
	s_nop 0
	global_load_lds_dwordx4 v[120:121], off

.LBB0_2152:
	s_cmp_ge_u32 s78, s66
	s_cbranch_scc1 .Lykb_xtail
	v_add_u32_e32 v0, s81, v208
	ds_read_b128 v[80:83], v0
	ds_read_b128 v[84:87], v0 offset:512
	ds_read_b128 v[6:9], v0 offset:2048
	ds_read_b128 v[112:115], v0 offset:2560
	ds_read_b128 v[10:13], v0 offset:4096
	ds_read_b128 v[116:119], v0 offset:4608
	ds_read_b128 v[2:5], v0 offset:6144
	ds_read_b128 v[120:123], v0 offset:6656
	s_and_b64 vcc, exec, s[8:9]
	s_cbranch_vccnz .LBB0_2161
	s_add_i32 s3, s79, s68
	s_mov_b32 m0, s3
	v_lshl_add_u64 v[14:15], v[170:171], 0, s[24:25]
	global_load_lds_dwordx4 v[170:171], off
	s_add_i32 m0, s3, 0x2000
	s_nop 0
	global_load_lds_dwordx4 v[14:15], off
	v_lshl_add_u64 v[14:15], v[170:171], 0, s[26:27]
	s_add_i32 m0, s3, 0x4000
	s_nop 0
	global_load_lds_dwordx4 v[14:15], off
	v_lshl_add_u64 v[14:15], v[170:171], 0, s[44:45]
	s_add_i32 m0, s3, 0x6000
	s_nop 0
	global_load_lds_dwordx4 v[14:15], off

.Lykb_ytop:
	s_cmp_ge_u32 s78, s66
	s_cbranch_scc1 .Lykb_ytail
	v_add_u32_e32 v0, s81, v208
	ds_read_b128 v[80:83], v0
	ds_read_b128 v[84:87], v0 offset:512
	ds_read_b128 v[6:9], v0 offset:2048
	ds_read_b128 v[112:115], v0 offset:2560
	ds_read_b128 v[10:13], v0 offset:4096
	ds_read_b128 v[116:119], v0 offset:4608
	ds_read_b128 v[2:5], v0 offset:6144
	ds_read_b128 v[120:123], v0 offset:6656
	v_pk_add_f32 v[14:15], v[168:169], 0 op_sel_hi:[1,0]
	v_cvt_pk_bf16_f32 v124, v168, v172
	v_pk_add_f32 v[14:15], v[172:173], v[14:15]
	v_cvt_pk_bf16_f32 v125, v174, v176
	v_pk_add_f32 v[14:15], v[174:175], v[14:15]
	v_cvt_pk_bf16_f32 v126, v178, v180
	v_pk_add_f32 v[14:15], v[176:177], v[14:15]
	v_cvt_pk_bf16_f32 v127, v182, v184
	v_pk_add_f32 v[14:15], v[178:179], v[14:15]
	v_cvt_pk_bf16_f32 v128, v186, v188
	v_pk_add_f32 v[14:15], v[180:181], v[14:15]
	v_cvt_pk_bf16_f32 v129, v190, v192
	v_pk_add_f32 v[14:15], v[182:183], v[14:15]
	v_cvt_pk_bf16_f32 v130, v194, v196
	v_pk_add_f32 v[14:15], v[184:185], v[14:15]
	v_cvt_pk_bf16_f32 v131, v198, v200
	v_pk_add_f32 v[14:15], v[186:187], v[14:15]
	v_cvt_pk_bf16_f32 v132, v169, v173
	v_pk_add_f32 v[14:15], v[188:189], v[14:15]
	v_cvt_pk_bf16_f32 v133, v175, v177
	v_pk_add_f32 v[14:15], v[190:191], v[14:15]
	v_cvt_pk_bf16_f32 v134, v179, v181
	v_pk_add_f32 v[14:15], v[192:193], v[14:15]
	v_cvt_pk_bf16_f32 v135, v183, v185
	v_pk_add_f32 v[14:15], v[194:195], v[14:15]
	v_cvt_pk_bf16_f32 v136, v187, v189
	v_pk_add_f32 v[14:15], v[196:197], v[14:15]
	v_cvt_pk_bf16_f32 v137, v191, v193
	v_pk_add_f32 v[14:15], v[198:199], v[14:15]
	v_cvt_pk_bf16_f32 v138, v195, v197
	v_pk_add_f32 v[14:15], v[200:201], v[14:15]
	v_cvt_pk_bf16_f32 v139, v199, v201
	v_add_f32_e32 v0, v14, v15
	s_waitcnt lgkmcnt(7)
	v_mfma_f32_32x32x16_bf16 v[96:111], v[80:83], v[144:147], 0
	v_add_u32_e32 v14, s80, v209
	s_waitcnt lgkmcnt(6)
	v_mfma_f32_32x32x16_bf16 v[80:95], v[84:87], v[144:147], 0
	s_waitcnt lgkmcnt(4)
	v_mfma_f32_32x32x16_bf16 v[80:95], v[112:115], v[148:151], v[80:95]
	v_mfma_f32_32x32x16_bf16 v[96:111], v[6:9], v[148:151], v[96:111]
	s_waitcnt lgkmcnt(2)
	v_mfma_f32_32x32x16_bf16 v[80:95], v[116:119], v[152:155], v[80:95]
	v_mfma_f32_32x32x16_bf16 v[96:111], v[10:13], v[152:155], v[96:111]
	ds_read_b128 v[6:9], v14 offset:16384
	ds_read_b128 v[10:13], v14 offset:16896
	ds_read_b128 v[112:115], v14 offset:17408
	ds_read_b128 v[116:119], v14 offset:17920
	s_waitcnt lgkmcnt(4)
	v_mfma_f32_32x32x16_bf16 v[80:95], v[120:123], v[156:159], v[80:95]
	v_mfma_f32_32x32x16_bf16 v[96:111], v[2:5], v[156:159], v[96:111]
	s_waitcnt vmcnt(0)
	s_barrier
	s_add_i32 s3, s78, 3
	s_cmp_lt_u32 s3, s69
	s_cbranch_scc0 .Lykb_ynodma
	s_add_i32 s3, s79, s68
	s_mov_b32 m0, s3
	v_lshl_add_u64 v[120:121], v[170:171], 0, s[24:25]
	global_load_lds_dwordx4 v[170:171], off
	s_add_i32 m0, s3, 0x2000
	s_nop 0
	global_load_lds_dwordx4 v[120:121], off
	v_lshl_add_u64 v[120:121], v[170:171], 0, s[26:27]
	s_add_i32 m0, s3, 0x4000
	s_nop 0
	global_load_lds_dwordx4 v[120:121], off
	v_lshl_add_u64 v[120:121], v[170:171], 0, s[44:45]
	s_add_i32 m0, s3, 0x6000
	s_nop 0
	global_load_lds_dwordx4 v[120:121], off
